# conv_prompt LayerNorm+silu: the wave's 4 rows processed together (DPP wave sums, shared sqrt/div, interleaved sigmoids), bit-identical arithmetic; on top of v30
# baseline (speedup 1.0000x reference)
.LBB0_571:
	ds_read_b128 v[100:103], v27
	ds_read_b128 v[104:107], v27 offset:1024
	ds_read_b128 v[108:111], v27 offset:16384
	ds_read_b128 v[112:115], v27 offset:17408
	ds_read_b128 v[116:119], v27 offset:32768
	ds_read_b128 v[120:123], v27 offset:33792
	ds_read_b128 v[124:127], v27 offset:49152
	ds_read_b128 v[128:131], v27 offset:50176
	s_mov_b64 s[32:33], 0x2000
	v_lshl_add_u64 v[160:161], v[18:19], 0, s[32:33]
	s_mov_b64 s[32:33], 0x4000
	v_lshl_add_u64 v[162:163], v[18:19], 0, s[32:33]
	s_mov_b64 s[32:33], 0x6000
	v_lshl_add_u64 v[164:165], v[18:19], 0, s[32:33]
	s_waitcnt lgkmcnt(0)
	v_add_f32_e32 v132, v101, v100
	v_add_f32_e32 v136, v109, v108
	v_add_f32_e32 v140, v117, v116
	v_add_f32_e32 v144, v125, v124
	v_add_f32_e32 v133, v102, v103
	v_add_f32_e32 v137, v110, v111
	v_add_f32_e32 v141, v118, v119
	v_add_f32_e32 v145, v126, v127
	v_add_f32_e32 v134, v106, v107
	v_add_f32_e32 v138, v114, v115
	v_add_f32_e32 v142, v122, v123
	v_add_f32_e32 v146, v130, v131
	v_add_f32_e32 v135, v104, v105
	v_add_f32_e32 v139, v112, v113
	v_add_f32_e32 v143, v120, v121
	v_add_f32_e32 v147, v128, v129
	v_add_f32_e32 v132, v132, v133
	v_add_f32_e32 v136, v136, v137
	v_add_f32_e32 v140, v140, v141
	v_add_f32_e32 v144, v144, v145
	v_add_f32_e32 v132, v132, v135
	v_add_f32_e32 v136, v136, v139
	v_add_f32_e32 v140, v140, v143
	v_add_f32_e32 v144, v144, v147
	v_add_f32_e32 v132, v134, v132
	v_add_f32_e32 v136, v138, v136
	v_add_f32_e32 v140, v142, v140
	v_add_f32_e32 v144, v146, v144
	v_add_f32_dpp v132, v132, v132 quad_perm:[1,0,3,2] row_mask:0xf bank_mask:0xf
	v_add_f32_dpp v136, v136, v136 quad_perm:[1,0,3,2] row_mask:0xf bank_mask:0xf
	v_add_f32_dpp v140, v140, v140 quad_perm:[1,0,3,2] row_mask:0xf bank_mask:0xf
	v_add_f32_dpp v144, v144, v144 quad_perm:[1,0,3,2] row_mask:0xf bank_mask:0xf
	v_add_f32_dpp v132, v132, v132 quad_perm:[2,3,0,1] row_mask:0xf bank_mask:0xf
	v_add_f32_dpp v136, v136, v136 quad_perm:[2,3,0,1] row_mask:0xf bank_mask:0xf
	v_add_f32_dpp v140, v140, v140 quad_perm:[2,3,0,1] row_mask:0xf bank_mask:0xf
	v_add_f32_dpp v144, v144, v144 quad_perm:[2,3,0,1] row_mask:0xf bank_mask:0xf
	v_add_f32_dpp v132, v132, v132 row_half_mirror row_mask:0xf bank_mask:0xf
	v_add_f32_dpp v136, v136, v136 row_half_mirror row_mask:0xf bank_mask:0xf
	v_add_f32_dpp v140, v140, v140 row_half_mirror row_mask:0xf bank_mask:0xf
	v_add_f32_dpp v144, v144, v144 row_half_mirror row_mask:0xf bank_mask:0xf
	v_add_f32_dpp v132, v132, v132 row_mirror row_mask:0xf bank_mask:0xf
	v_add_f32_dpp v136, v136, v136 row_mirror row_mask:0xf bank_mask:0xf
	v_add_f32_dpp v140, v140, v140 row_mirror row_mask:0xf bank_mask:0xf
	v_add_f32_dpp v144, v144, v144 row_mirror row_mask:0xf bank_mask:0xf
	v_readlane_b32 s8, v132, 0
	v_readlane_b32 s9, v132, 16
	v_readlane_b32 s10, v132, 32
	v_readlane_b32 s11, v132, 48
	v_readlane_b32 s12, v136, 0
	v_readlane_b32 s13, v136, 16
	v_readlane_b32 s14, v136, 32
	v_readlane_b32 s15, v136, 48
	v_readlane_b32 s42, v140, 0
	v_readlane_b32 s43, v140, 16
	v_readlane_b32 s44, v140, 32
	v_readlane_b32 s45, v140, 48
	v_readlane_b32 s46, v144, 0
	v_readlane_b32 s47, v144, 16
	v_readlane_b32 s48, v144, 32
	v_readlane_b32 s49, v144, 48
	v_mov_b32_e32 v133, s9
	v_mov_b32_e32 v134, s11
	v_mov_b32_e32 v137, s13
	v_mov_b32_e32 v138, s15
	v_mov_b32_e32 v141, s43
	v_mov_b32_e32 v142, s45
	v_mov_b32_e32 v145, s47
	v_mov_b32_e32 v146, s49
	v_add_f32_e32 v133, s8, v133
	v_add_f32_e32 v134, s10, v134
	v_add_f32_e32 v137, s12, v137
	v_add_f32_e32 v138, s14, v138
	v_add_f32_e32 v141, s42, v141
	v_add_f32_e32 v142, s44, v142
	v_add_f32_e32 v145, s46, v145
	v_add_f32_e32 v146, s48, v146
	v_add_f32_e32 v132, v133, v134
	v_add_f32_e32 v136, v137, v138
	v_add_f32_e32 v140, v141, v142
	v_add_f32_e32 v144, v145, v146
	v_fmamk_f32 v100, v132, 0xbb000000, v100
	v_fmamk_f32 v108, v136, 0xbb000000, v108
	v_fmamk_f32 v116, v140, 0xbb000000, v116
	v_fmamk_f32 v124, v144, 0xbb000000, v124
	v_fmamk_f32 v101, v132, 0xbb000000, v101
	v_fmamk_f32 v109, v136, 0xbb000000, v109
	v_fmamk_f32 v117, v140, 0xbb000000, v117
	v_fmamk_f32 v125, v144, 0xbb000000, v125
	v_fmamk_f32 v102, v132, 0xbb000000, v102
	v_fmamk_f32 v110, v136, 0xbb000000, v110
	v_fmamk_f32 v118, v140, 0xbb000000, v118
	v_fmamk_f32 v126, v144, 0xbb000000, v126
	v_fmamk_f32 v103, v132, 0xbb000000, v103
	v_fmamk_f32 v111, v136, 0xbb000000, v111
	v_fmamk_f32 v119, v140, 0xbb000000, v119
	v_fmamk_f32 v127, v144, 0xbb000000, v127
	v_fmamk_f32 v104, v132, 0xbb000000, v104
	v_fmamk_f32 v112, v136, 0xbb000000, v112
	v_fmamk_f32 v120, v140, 0xbb000000, v120
	v_fmamk_f32 v128, v144, 0xbb000000, v128
	v_fmamk_f32 v105, v132, 0xbb000000, v105
	v_fmamk_f32 v113, v136, 0xbb000000, v113
	v_fmamk_f32 v121, v140, 0xbb000000, v121
	v_fmamk_f32 v129, v144, 0xbb000000, v129
	v_fmamk_f32 v106, v132, 0xbb000000, v106
	v_fmamk_f32 v114, v136, 0xbb000000, v114
	v_fmamk_f32 v122, v140, 0xbb000000, v122
	v_fmamk_f32 v130, v144, 0xbb000000, v130
	v_fmamk_f32 v107, v132, 0xbb000000, v107
	v_fmamk_f32 v115, v136, 0xbb000000, v115
	v_fmamk_f32 v123, v140, 0xbb000000, v123
	v_fmamk_f32 v131, v144, 0xbb000000, v131
	v_mul_f32_e32 v132, v101, v101
	v_mul_f32_e32 v136, v109, v109
	v_mul_f32_e32 v140, v117, v117
	v_mul_f32_e32 v144, v125, v125
	v_mul_f32_e32 v133, v103, v103
	v_mul_f32_e32 v137, v111, v111
	v_mul_f32_e32 v141, v119, v119
	v_mul_f32_e32 v145, v127, v127
	v_fmac_f32_e32 v132, v100, v100
	v_fmac_f32_e32 v136, v108, v108
	v_fmac_f32_e32 v140, v116, v116
	v_fmac_f32_e32 v144, v124, v124
	v_fmac_f32_e32 v133, v102, v102
	v_fmac_f32_e32 v137, v110, v110
	v_fmac_f32_e32 v141, v118, v118
	v_fmac_f32_e32 v145, v126, v126
	v_add_f32_e32 v135, v132, v133
	v_add_f32_e32 v139, v136, v137
	v_add_f32_e32 v143, v140, v141
	v_add_f32_e32 v147, v144, v145
	v_mul_f32_e32 v132, v106, v106
	v_mul_f32_e32 v136, v114, v114
	v_mul_f32_e32 v140, v122, v122
	v_mul_f32_e32 v144, v130, v130
	v_mul_f32_e32 v133, v107, v107
	v_mul_f32_e32 v137, v115, v115
	v_mul_f32_e32 v141, v123, v123
	v_mul_f32_e32 v145, v131, v131
	v_mul_f32_e32 v134, v104, v104
	v_mul_f32_e32 v138, v112, v112
	v_mul_f32_e32 v142, v120, v120
	v_mul_f32_e32 v146, v128, v128
	v_mul_f32_e32 v180, v105, v105
	v_mul_f32_e32 v188, v113, v113
	v_mul_f32_e32 v196, v121, v121
	v_mul_f32_e32 v204, v129, v129
	v_add_f32_e32 v132, v132, v133
	v_add_f32_e32 v136, v136, v137
	v_add_f32_e32 v140, v140, v141
	v_add_f32_e32 v144, v144, v145
	v_add_f32_e32 v134, v134, v180
	v_add_f32_e32 v138, v138, v188
	v_add_f32_e32 v142, v142, v196
	v_add_f32_e32 v146, v146, v204
	v_add_f32_e32 v134, v134, v135
	v_add_f32_e32 v138, v138, v139
	v_add_f32_e32 v142, v142, v143
	v_add_f32_e32 v146, v146, v147
	v_add_f32_e32 v132, v132, v134
	v_add_f32_e32 v136, v136, v138
	v_add_f32_e32 v140, v140, v142
	v_add_f32_e32 v144, v144, v146
	v_add_f32_dpp v132, v132, v132 quad_perm:[1,0,3,2] row_mask:0xf bank_mask:0xf
	v_add_f32_dpp v136, v136, v136 quad_perm:[1,0,3,2] row_mask:0xf bank_mask:0xf
	v_add_f32_dpp v140, v140, v140 quad_perm:[1,0,3,2] row_mask:0xf bank_mask:0xf
	v_add_f32_dpp v144, v144, v144 quad_perm:[1,0,3,2] row_mask:0xf bank_mask:0xf
	v_add_f32_dpp v132, v132, v132 quad_perm:[2,3,0,1] row_mask:0xf bank_mask:0xf
	v_add_f32_dpp v136, v136, v136 quad_perm:[2,3,0,1] row_mask:0xf bank_mask:0xf
	v_add_f32_dpp v140, v140, v140 quad_perm:[2,3,0,1] row_mask:0xf bank_mask:0xf
	v_add_f32_dpp v144, v144, v144 quad_perm:[2,3,0,1] row_mask:0xf bank_mask:0xf
	v_add_f32_dpp v132, v132, v132 row_half_mirror row_mask:0xf bank_mask:0xf
	v_add_f32_dpp v136, v136, v136 row_half_mirror row_mask:0xf bank_mask:0xf
	v_add_f32_dpp v140, v140, v140 row_half_mirror row_mask:0xf bank_mask:0xf
	v_add_f32_dpp v144, v144, v144 row_half_mirror row_mask:0xf bank_mask:0xf
	v_add_f32_dpp v132, v132, v132 row_mirror row_mask:0xf bank_mask:0xf
	v_add_f32_dpp v136, v136, v136 row_mirror row_mask:0xf bank_mask:0xf
	v_add_f32_dpp v140, v140, v140 row_mirror row_mask:0xf bank_mask:0xf
	v_add_f32_dpp v144, v144, v144 row_mirror row_mask:0xf bank_mask:0xf
	v_readlane_b32 s8, v132, 0
	v_readlane_b32 s9, v132, 16
	v_readlane_b32 s10, v132, 32
	v_readlane_b32 s11, v132, 48
	v_readlane_b32 s12, v136, 0
	v_readlane_b32 s13, v136, 16
	v_readlane_b32 s14, v136, 32
	v_readlane_b32 s15, v136, 48
	v_readlane_b32 s42, v140, 0
	v_readlane_b32 s43, v140, 16
	v_readlane_b32 s44, v140, 32
	v_readlane_b32 s45, v140, 48
	v_readlane_b32 s46, v144, 0
	v_readlane_b32 s47, v144, 16
	v_readlane_b32 s48, v144, 32
	v_readlane_b32 s49, v144, 48
	v_mov_b32_e32 v133, s9
	v_mov_b32_e32 v134, s11
	v_mov_b32_e32 v137, s13
	v_mov_b32_e32 v138, s15
	v_mov_b32_e32 v141, s43
	v_mov_b32_e32 v142, s45
	v_mov_b32_e32 v145, s47
	v_mov_b32_e32 v146, s49
	v_add_f32_e32 v133, s8, v133
	v_add_f32_e32 v134, s10, v134
	v_add_f32_e32 v137, s12, v137
	v_add_f32_e32 v138, s14, v138
	v_add_f32_e32 v141, s42, v141
	v_add_f32_e32 v142, s44, v142
	v_add_f32_e32 v145, s46, v145
	v_add_f32_e32 v146, s48, v146
	v_add_f32_e32 v132, v133, v134
	v_add_f32_e32 v136, v137, v138
	v_add_f32_e32 v140, v141, v142
	v_add_f32_e32 v144, v145, v146
	v_fmamk_f32 v132, v132, 0x3b000000, v75
	v_fmamk_f32 v136, v136, 0x3b000000, v75
	v_fmamk_f32 v140, v140, 0x3b000000, v75
	v_fmamk_f32 v144, v144, 0x3b000000, v75
	v_mov_b32_e32 v148, v132
	v_readfirstlane_b32 s51, v136
	v_readfirstlane_b32 s52, v140
	v_readfirstlane_b32 s53, v144
	s_nop 1
	v_writelane_b32 v148, s51, 1
	v_writelane_b32 v148, s52, 2
	v_writelane_b32 v148, s53, 3
	v_cmp_gt_f32_e32 vcc, s65, v148
	v_mul_f32_e32 v149, 0x4f800000, v148
	s_nop 0
	v_cndmask_b32_e32 v148, v148, v149, vcc
	v_sqrt_f32_e32 v149, v148
	s_nop 0
	v_add_u32_e32 v150, -1, v149
	v_fma_f32 v151, -v150, v149, v148
	v_cmp_ge_f32_e64 s[32:33], 0, v151
	v_add_u32_e32 v151, 1, v149
	s_nop 0
	v_cndmask_b32_e64 v150, v149, v150, s[32:33]
	v_fma_f32 v149, -v151, v149, v148
	v_cmp_lt_f32_e64 s[32:33], 0, v149
	s_nop 1
	v_cndmask_b32_e64 v149, v150, v151, s[32:33]
	v_mul_f32_e32 v150, 0x37800000, v149
	v_cndmask_b32_e32 v149, v149, v150, vcc
	v_cmp_class_f32_e32 vcc, v148, v76
	s_nop 1
	v_cndmask_b32_e32 v148, v149, v148, vcc
	v_div_scale_f32 v149, s[32:33], v148, v148, 1.0
	v_rcp_f32_e32 v150, v149
	s_nop 0
	v_fma_f32 v151, -v149, v150, 1.0
	v_fmac_f32_e32 v150, v151, v150
	v_div_scale_f32 v151, vcc, 1.0, v148, 1.0
	v_mul_f32_e32 v152, v151, v150
	v_fma_f32 v153, -v149, v152, v151
	v_fmac_f32_e32 v152, v153, v150
	v_fma_f32 v149, -v149, v152, v151
	v_div_fmas_f32 v149, v149, v150, v152
	v_div_fixup_f32 v148, v149, v148, 1.0
	s_nop 0
	v_readlane_b32 s50, v148, 0
	v_readlane_b32 s51, v148, 1
	v_readlane_b32 s52, v148, 2
	v_readlane_b32 s53, v148, 3
	s_nop 1
	v_mul_f32_e32 v100, s50, v100
	v_mul_f32_e32 v108, s51, v108
	v_mul_f32_e32 v116, s52, v116
	v_mul_f32_e32 v124, s53, v124
	v_mul_f32_e32 v101, s50, v101
	v_mul_f32_e32 v109, s51, v109
	v_mul_f32_e32 v117, s52, v117
	v_mul_f32_e32 v125, s53, v125
	v_mul_f32_e32 v102, s50, v102
	v_mul_f32_e32 v110, s51, v110
	v_mul_f32_e32 v118, s52, v118
	v_mul_f32_e32 v126, s53, v126
	v_mul_f32_e32 v103, s50, v103
	v_mul_f32_e32 v111, s51, v111
	v_mul_f32_e32 v119, s52, v119
	v_mul_f32_e32 v127, s53, v127
	v_mul_f32_e32 v104, s50, v104
	v_mul_f32_e32 v112, s51, v112
	v_mul_f32_e32 v120, s52, v120
	v_mul_f32_e32 v128, s53, v128
	v_mul_f32_e32 v105, s50, v105
	v_mul_f32_e32 v113, s51, v113
	v_mul_f32_e32 v121, s52, v121
	v_mul_f32_e32 v129, s53, v129
	v_mul_f32_e32 v106, s50, v106
	v_mul_f32_e32 v114, s51, v114
	v_mul_f32_e32 v122, s52, v122
	v_mul_f32_e32 v130, s53, v130
	v_mul_f32_e32 v107, s50, v107
	v_mul_f32_e32 v115, s51, v115
	v_mul_f32_e32 v123, s52, v123
	v_mul_f32_e32 v131, s53, v131
	v_pk_fma_f32 v[100:101], v[0:1], v[100:101], v[4:5]
	v_pk_fma_f32 v[108:109], v[0:1], v[108:109], v[4:5]
	v_pk_fma_f32 v[116:117], v[0:1], v[116:117], v[4:5]
	v_pk_fma_f32 v[124:125], v[0:1], v[124:125], v[4:5]
	v_pk_fma_f32 v[102:103], v[2:3], v[102:103], v[6:7]
	v_pk_fma_f32 v[110:111], v[2:3], v[110:111], v[6:7]
	v_pk_fma_f32 v[118:119], v[2:3], v[118:119], v[6:7]
	v_pk_fma_f32 v[126:127], v[2:3], v[126:127], v[6:7]
	v_pk_fma_f32 v[104:105], v[8:9], v[104:105], v[12:13]
	v_pk_fma_f32 v[112:113], v[8:9], v[112:113], v[12:13]
	v_pk_fma_f32 v[120:121], v[8:9], v[120:121], v[12:13]
	v_pk_fma_f32 v[128:129], v[8:9], v[128:129], v[12:13]
	v_pk_fma_f32 v[106:107], v[10:11], v[106:107], v[14:15]
	v_pk_fma_f32 v[114:115], v[10:11], v[114:115], v[14:15]
	v_pk_fma_f32 v[122:123], v[10:11], v[122:123], v[14:15]
	v_pk_fma_f32 v[130:131], v[10:11], v[130:131], v[14:15]
	v_mul_f32_e32 v180, 0xbfb8aa3b, v100
	v_mul_f32_e32 v181, 0xbfb8aa3b, v101
	v_mul_f32_e32 v182, 0xbfb8aa3b, v102
	v_mul_f32_e32 v183, 0xbfb8aa3b, v103
	v_mul_f32_e32 v188, 0xbfb8aa3b, v108
	v_mul_f32_e32 v189, 0xbfb8aa3b, v109
	v_mul_f32_e32 v190, 0xbfb8aa3b, v110
	v_mul_f32_e32 v191, 0xbfb8aa3b, v111
	v_mul_f32_e32 v196, 0xbfb8aa3b, v116
	v_mul_f32_e32 v197, 0xbfb8aa3b, v117
	v_mul_f32_e32 v198, 0xbfb8aa3b, v118
	v_mul_f32_e32 v199, 0xbfb8aa3b, v119
	v_mul_f32_e32 v204, 0xbfb8aa3b, v124
	v_mul_f32_e32 v205, 0xbfb8aa3b, v125
	v_mul_f32_e32 v206, 0xbfb8aa3b, v126
	v_mul_f32_e32 v207, 0xbfb8aa3b, v127
	v_mul_f32_e32 v184, 0xbfb8aa3b, v104
	v_mul_f32_e32 v185, 0xbfb8aa3b, v105
	v_mul_f32_e32 v186, 0xbfb8aa3b, v106
	v_mul_f32_e32 v187, 0xbfb8aa3b, v107
	v_mul_f32_e32 v192, 0xbfb8aa3b, v112
	v_mul_f32_e32 v193, 0xbfb8aa3b, v113
	v_mul_f32_e32 v194, 0xbfb8aa3b, v114
	v_mul_f32_e32 v195, 0xbfb8aa3b, v115
	v_mul_f32_e32 v200, 0xbfb8aa3b, v120
	v_mul_f32_e32 v201, 0xbfb8aa3b, v121
	v_mul_f32_e32 v202, 0xbfb8aa3b, v122
	v_mul_f32_e32 v203, 0xbfb8aa3b, v123
	v_mul_f32_e32 v208, 0xbfb8aa3b, v128
	v_mul_f32_e32 v209, 0xbfb8aa3b, v129
	v_mul_f32_e32 v210, 0xbfb8aa3b, v130
	v_mul_f32_e32 v211, 0xbfb8aa3b, v131
	v_exp_f32_e32 v180, v180
	v_exp_f32_e32 v181, v181
	v_exp_f32_e32 v182, v182
	v_exp_f32_e32 v183, v183
	v_exp_f32_e32 v188, v188
	v_exp_f32_e32 v189, v189
	v_exp_f32_e32 v190, v190
	v_exp_f32_e32 v191, v191
	v_exp_f32_e32 v196, v196
	v_exp_f32_e32 v197, v197
	v_exp_f32_e32 v198, v198
	v_exp_f32_e32 v199, v199
	v_exp_f32_e32 v204, v204
	v_exp_f32_e32 v205, v205
	v_exp_f32_e32 v206, v206
	v_exp_f32_e32 v207, v207
	v_exp_f32_e32 v184, v184
	v_exp_f32_e32 v185, v185
	v_exp_f32_e32 v186, v186
	v_exp_f32_e32 v187, v187
	v_exp_f32_e32 v192, v192
	v_exp_f32_e32 v193, v193
	v_exp_f32_e32 v194, v194
	v_exp_f32_e32 v195, v195
	v_exp_f32_e32 v200, v200
	v_exp_f32_e32 v201, v201
	v_exp_f32_e32 v202, v202
	v_exp_f32_e32 v203, v203
	v_exp_f32_e32 v208, v208
	v_exp_f32_e32 v209, v209
	v_exp_f32_e32 v210, v210
	v_exp_f32_e32 v211, v211
	v_add_f32_e32 v180, 1.0, v180
	v_add_f32_e32 v181, 1.0, v181
	v_add_f32_e32 v182, 1.0, v182
	v_add_f32_e32 v183, 1.0, v183
	v_add_f32_e32 v188, 1.0, v188
	v_add_f32_e32 v189, 1.0, v189
	v_add_f32_e32 v190, 1.0, v190
	v_add_f32_e32 v191, 1.0, v191
	v_add_f32_e32 v196, 1.0, v196
	v_add_f32_e32 v197, 1.0, v197
	v_add_f32_e32 v198, 1.0, v198
	v_add_f32_e32 v199, 1.0, v199
	v_add_f32_e32 v204, 1.0, v204
	v_add_f32_e32 v205, 1.0, v205
	v_add_f32_e32 v206, 1.0, v206
	v_add_f32_e32 v207, 1.0, v207
	v_add_f32_e32 v184, 1.0, v184
	v_add_f32_e32 v185, 1.0, v185
	v_add_f32_e32 v186, 1.0, v186
	v_add_f32_e32 v187, 1.0, v187
	v_add_f32_e32 v192, 1.0, v192
	v_add_f32_e32 v193, 1.0, v193
	v_add_f32_e32 v194, 1.0, v194
	v_add_f32_e32 v195, 1.0, v195
	v_add_f32_e32 v200, 1.0, v200
	v_add_f32_e32 v201, 1.0, v201
	v_add_f32_e32 v202, 1.0, v202
	v_add_f32_e32 v203, 1.0, v203
	v_add_f32_e32 v208, 1.0, v208
	v_add_f32_e32 v209, 1.0, v209
	v_add_f32_e32 v210, 1.0, v210
	v_add_f32_e32 v211, 1.0, v211
	v_rcp_f32_e32 v180, v180
	v_rcp_f32_e32 v181, v181
	v_rcp_f32_e32 v182, v182
	v_rcp_f32_e32 v183, v183
	v_rcp_f32_e32 v188, v188
	v_rcp_f32_e32 v189, v189
	v_rcp_f32_e32 v190, v190
	v_rcp_f32_e32 v191, v191
	v_rcp_f32_e32 v196, v196
	v_rcp_f32_e32 v197, v197
	v_rcp_f32_e32 v198, v198
	v_rcp_f32_e32 v199, v199
	v_rcp_f32_e32 v204, v204
	v_rcp_f32_e32 v205, v205
	v_rcp_f32_e32 v206, v206
	v_rcp_f32_e32 v207, v207
	v_rcp_f32_e32 v184, v184
	v_rcp_f32_e32 v185, v185
	v_rcp_f32_e32 v186, v186
	v_rcp_f32_e32 v187, v187
	v_rcp_f32_e32 v192, v192
	v_rcp_f32_e32 v193, v193
	v_rcp_f32_e32 v194, v194
	v_rcp_f32_e32 v195, v195
	v_rcp_f32_e32 v200, v200
	v_rcp_f32_e32 v201, v201
	v_rcp_f32_e32 v202, v202
	v_rcp_f32_e32 v203, v203
	v_rcp_f32_e32 v208, v208
	v_rcp_f32_e32 v209, v209
	v_rcp_f32_e32 v210, v210
	v_rcp_f32_e32 v211, v211
	v_mul_f32_e32 v100, v100, v180
	v_mul_f32_e32 v101, v101, v181
	v_mul_f32_e32 v102, v102, v182
	v_mul_f32_e32 v103, v103, v183
	v_mul_f32_e32 v108, v108, v188
	v_mul_f32_e32 v109, v109, v189
	v_mul_f32_e32 v110, v110, v190
	v_mul_f32_e32 v111, v111, v191
	v_mul_f32_e32 v116, v116, v196
	v_mul_f32_e32 v117, v117, v197
	v_mul_f32_e32 v118, v118, v198
	v_mul_f32_e32 v119, v119, v199
	v_mul_f32_e32 v124, v124, v204
	v_mul_f32_e32 v125, v125, v205
	v_mul_f32_e32 v126, v126, v206
	v_mul_f32_e32 v127, v127, v207
	v_mul_f32_e32 v104, v104, v184
	v_mul_f32_e32 v105, v105, v185
	v_mul_f32_e32 v106, v106, v186
	v_mul_f32_e32 v107, v107, v187
	v_mul_f32_e32 v112, v112, v192
	v_mul_f32_e32 v113, v113, v193
	v_mul_f32_e32 v114, v114, v194
	v_mul_f32_e32 v115, v115, v195
	v_mul_f32_e32 v120, v120, v200
	v_mul_f32_e32 v121, v121, v201
	v_mul_f32_e32 v122, v122, v202
	v_mul_f32_e32 v123, v123, v203
	v_mul_f32_e32 v128, v128, v208
	v_mul_f32_e32 v129, v129, v209
	v_mul_f32_e32 v130, v130, v210
	v_mul_f32_e32 v131, v131, v211
	v_cvt_pk_bf16_f32 v180, v100, v101
	v_cvt_pk_bf16_f32 v181, v102, v103
	v_cvt_pk_bf16_f32 v182, v104, v105
	v_cvt_pk_bf16_f32 v183, v106, v107
	v_cvt_pk_bf16_f32 v188, v108, v109
	v_cvt_pk_bf16_f32 v189, v110, v111
	v_cvt_pk_bf16_f32 v190, v112, v113
	v_cvt_pk_bf16_f32 v191, v114, v115
	v_cvt_pk_bf16_f32 v196, v116, v117
	v_cvt_pk_bf16_f32 v197, v118, v119
	v_cvt_pk_bf16_f32 v198, v120, v121
	v_cvt_pk_bf16_f32 v199, v122, v123
	v_cvt_pk_bf16_f32 v204, v124, v125
	v_cvt_pk_bf16_f32 v205, v126, v127
	v_cvt_pk_bf16_f32 v206, v128, v129
	v_cvt_pk_bf16_f32 v207, v130, v131
	global_store_dwordx2 v[18:19], v[180:181], off
	global_store_dwordx2 v[18:19], v[182:183], off offset:512
	global_store_dwordx2 v[160:161], v[188:189], off
	global_store_dwordx2 v[160:161], v[190:191], off offset:512
	global_store_dwordx2 v[162:163], v[196:197], off
	global_store_dwordx2 v[162:163], v[198:199], off offset:512
	global_store_dwordx2 v[164:165], v[204:205], off
	global_store_dwordx2 v[164:165], v[206:207], off offset:512
